# SchedB P4 tiles also dealt in reverse (L -> 959-L) on top of reversed SchedA
# speedup vs baseline: 1.0098x; 1.0098x over previous
;         if (L < 960) { tile_map(L, 120, 8, u.pm, u.pn); u.type = 1; } else { tile_map(L - 960, 8, 8, u.pm, u.pn); u.pm += 128; u.type = 0; }
.LBB0_876:
	s_or_b64 exec, exec, s[2:3]
	s_add_u32 s68, s26, 0xc1e0000
	v_mov_b32_e32 v10, v0
	s_addc_u32 s69, s27, 0
	s_waitcnt lgkmcnt(0)
	s_barrier
	s_andn2_b64 vcc, exec, s[16:17]
	v_readfirstlane_b32 s48, v10
	s_cbranch_vccnz .LBB0_914
	s_cmpk_gt_i32 s8, 0x3bf
	s_cbranch_scc1 .LBB0_879
	s_sub_i32 s98, 0x3bf, s8
	s_ashr_i32 s0, s98, 31
	s_lshr_b32 s0, s0, 29
	s_add_i32 s0, s98, s0
	s_and_b32 s1, s0, -8
	s_sub_i32 s1, s98, s1
	s_cmp_lt_i32 s1, 0
	s_movk_i32 s2, 0x79
	s_cselect_b32 s2, s2, 0x78
	s_mul_i32 s1, s2, s1
	s_ashr_i32 s0, s0, 3
	s_add_i32 s0, s1, s0
	s_ashr_i32 s1, s0, 31
	s_lshr_b32 s1, s1, 26
	s_add_i32 s1, s0, s1
	s_ashr_i32 s2, s1, 6
	s_andn2_b32 s1, s1, 63
	s_sub_i32 s0, s0, s1
	s_bfe_i32 s1, s0, 0x80000
	s_bfe_u32 s1, s1, 0x3000c
	s_add_i32 s1, s0, s1
	s_bfe_i32 s3, s1, 0x80000
	s_and_b32 s1, s1, 0xf8
	s_sub_i32 s0, s0, s1
	s_lshl_b32 s2, s2, 3
	s_sext_i32_i16 s3, s3
	s_sext_i32_i8 s0, s0
	s_add_i32 s65, s2, s0
	s_ashr_i32 s64, s3, 3
	s_mov_b64 s[2:3], s[12:13]
	s_mov_b32 s67, 1
	s_mov_b64 s[16:17], 0xc1e0000
	s_cbranch_execz .LBB0_880
	s_branch .LBB0_881

;         if (L < 960) { tile_map(L, 120, 8, u.pm, u.pn); u.type = 1; } else { tile_map(L - 960, 8, 8, u.pm, u.pn); u.pm += 128; u.type = 0; }
.LBB0_889:
	s_andn2_b64 vcc, exec, s[2:3]
	s_mov_b32 s63, 0
	s_cbranch_vccnz .LBB0_891
	s_sub_i32 s0, 0x3bf, s0
	s_ashr_i32 s1, s0, 31
	s_lshr_b32 s1, s1, 29
	s_add_i32 s1, s0, s1
	s_ashr_i32 s2, s1, 3
	s_and_b32 s1, s1, -8
	s_sub_i32 s0, s0, s1
	s_cmp_lt_i32 s0, 0
	s_cselect_b32 s1, s56, 0x78
	s_mul_i32 s0, s1, s0
	s_add_i32 s0, s0, s2
	s_ashr_i32 s1, s0, 31
	s_lshr_b32 s1, s1, 26
	s_add_i32 s1, s0, s1
	s_ashr_i32 s2, s1, 6
	s_and_b32 s1, s1, 0xffc0
	s_sub_i32 s0, s0, s1
	s_bfe_i32 s1, s0, 0x80000
	s_bfe_u32 s1, s1, 0x3000c
	s_add_i32 s1, s0, s1
	s_bfe_i32 s3, s1, 0x80000
	s_and_b32 s1, s1, 0xf8
	s_sub_i32 s0, s0, s1
	s_lshl_b32 s2, s2, 3
	s_sext_i32_i16 s3, s3
	s_sext_i32_i8 s0, s0
	s_add_i32 s62, s2, s0
	s_ashr_i32 s61, s3, 3
	s_mov_b32 s63, 1
